# v13 + residual-tile cache prefetch (4 dword touches per lane at each tile-loop header) in P3, P10, P13
# baseline (speedup 1.0000x reference)
;     DEV void operator()(const f32x4 (&acc)[2][2][4][2], const Unit& u, int wr, int wc, int fr, int fq) const {
;     ...
;         const bool lat = u.pm < MLAT / 256; const int b = lat ? (u.pm >> 4) : 16;
;         const float* res = lat ? res_lat : res_ctx; float* out = lat ? out_lat : out_ctx;
;         const int grow0 = u.pm * 256 + wr * 64 + fr, row0 = (lat ? grow0 : grow0 - MLAT), col0 = u.pn * 256 + wc * 32 + (PERM ? 8 : 4) * fq;
;         float ss[8];
; #pragma unroll
;         for (int i = 0; i < 8; ++i) ss[i] = 0.f;
; #pragma unroll
;         for (int bj = 0; bj < 2; ++bj) {
;             f32x4 gv[2], gs[2];
; #pragma unroll
;             for (int n = 0; n < 2; ++n) { gv[n] = *(const f32x4*)(mod + (size_t)b * NMOD + gate_i * D + col0 + bj * 128 + NS * n) * coef;
;                 if (has_xn) gs[n] = *(const f32x4*)(g + col0 + bj * 128 + 4 * n) * (*(const f32x4*)(mod + (size_t)b * NMOD + scale_i * D + col0 + bj * 128 + 4 * n) + 1.f); }
; #pragma unroll
;             for (int ai = 0; ai < 2; ++ai)
; #pragma unroll
;                 for (int m = 0; m < 4; ++m) {
;                     const size_t p = (size_t)(row0 + ai * 128 + m * 16) * D + col0 + bj * 128;
;                     const f32x4 r0 = *(const f32x4*)(res + p), r1 = *(const f32x4*)(res + p + NS);
.LBB0_372:
	s_cmpk_ge_i32 s33, 0x100
	s_cbranch_scc1 .Lpf_skip_p3
	s_lshl_b32 s100, s33, 8
	s_add_u32 s100, s100, s66
	v_lshrrev_b32_e32 v252, 1, v226
	v_lshlrev_b32_e32 v252, 4, v252
	v_add_u32_e32 v252, v252, v147
	v_add_u32_e32 v252, s100, v252
	s_lshl_b32 s101, s82, 8
	s_or_b32 s101, s101, s67
	s_lshl_b32 s101, s101, 2
	v_and_b32_e32 v253, 1, v226
	v_lshlrev_b32_e32 v253, 9, v253
	v_add_u32_e32 v253, s101, v253
	v_lshl_add_u32 v252, v252, 12, v253
	global_load_dword v255, v252, s[68:69]
	s_add_u32 s98, s68, 0x20000
	s_addc_u32 s99, s69, 0
	global_load_dword v255, v252, s[98:99]
	s_add_u32 s98, s68, 0x80000
	s_addc_u32 s99, s69, 0
	global_load_dword v255, v252, s[98:99]
	s_add_u32 s98, s68, 0xa0000
	s_addc_u32 s99, s69, 0
	global_load_dword v255, v252, s[98:99]

;     __host__ __device__ bool next(int i, Unit& u) const {
;         const long L = (long)i * G + c; if (L >= nwg) return false;
;         int wgid = (int)L; { const int q = nwg / NXCD, r = nwg % NXCD, xcd = wgid % NXCD, off = wgid / NXCD; wgid = (xcd < r ? xcd * (q + 1) : r * (q + 1) + (xcd - r) * q) + off; }
;         const int nig = WGM * nN, gid = wgid / nig, fm = gid * WGM, gsz = (nM - fm) < WGM ? (nM - fm) : WGM;
;         u.pm = fm + ((wgid % nig) % gsz); u.pn = (wgid % nig) / gsz; return true;
;     DEV void operator()(const f32x4 (&acc)[2][2][4][2], const Unit& u, int wr, int wc, int fr, int fq) const {
;     ...
;                     const size_t p = (size_t)(row0 + ai * 128 + m * 16) * D + col0 + bj * 128;
;                     const f32x4 r0 = *(const f32x4*)(res + p), r1 = *(const f32x4*)(res + p + NS);
.LBB0_1789:
	s_lshl_b32 s100, s0, 8
	s_add_u32 s100, s100, s48
	v_lshrrev_b32_e32 v252, 1, v220
	v_lshlrev_b32_e32 v252, 4, v252
	v_add_u32_e32 v252, v252, v147
	v_add_u32_e32 v252, s100, v252
	s_lshl_b32 s101, s30, 8
	s_or_b32 s101, s101, s49
	s_lshl_b32 s101, s101, 2
	v_and_b32_e32 v253, 1, v220
	v_lshlrev_b32_e32 v253, 9, v253
	v_add_u32_e32 v253, s101, v253
	v_lshl_add_u32 v252, v252, 12, v253
	global_load_dword v255, v252, s[86:87]
	s_add_u32 s98, s86, 0x20000
	s_addc_u32 s99, s87, 0
	global_load_dword v255, v252, s[98:99]
	s_add_u32 s98, s86, 0x80000
	s_addc_u32 s99, s87, 0
	global_load_dword v255, v252, s[98:99]
	s_add_u32 s98, s86, 0xa0000
	s_addc_u32 s99, s87, 0
	global_load_dword v255, v252, s[98:99]
	s_add_i32 s47, s47, 1
	s_mul_i32 s1, s47, s53
	s_mul_hi_u32 s4, s47, s50
	s_add_i32 s4, s4, s1
	s_mul_i32 s1, s47, s50
	s_add_u32 s26, s1, s2
	s_addc_u32 s27, s4, s54
	v_cmp_gt_i64_e32 vcc, s[26:27], v[154:155]
	v_cmp_lt_i64_e64 s[4:5], s[26:27], v[152:153]
	s_cbranch_vccnz .LBB0_1795
	s_ashr_i32 s1, s26, 31
	s_lshr_b32 s1, s1, 29
	s_add_i32 s1, s26, s1
	s_and_b32 s22, s1, -8
	s_sub_i32 s24, s26, s22
	s_cmp_gt_i32 s24, -1
	s_mov_b64 s[22:23], -1
	s_cbranch_scc0 .LBB0_1792
	s_lshl_b32 s25, s24, 7
	s_mov_b64 s[22:23], 0

;     __host__ __device__ bool next(int i, Unit& u) const {
;         const long L = (long)i * G + c; if (L >= nwg) return false;
;         int wgid = (int)L; { const int q = nwg / NXCD, r = nwg % NXCD, xcd = wgid % NXCD, off = wgid / NXCD; wgid = (xcd < r ? xcd * (q + 1) : r * (q + 1) + (xcd - r) * q) + off; }
;         const int nig = WGM * nN, gid = wgid / nig, fm = gid * WGM, gsz = (nM - fm) < WGM ? (nM - fm) : WGM;
;         u.pm = fm + ((wgid % nig) % gsz); u.pn = (wgid % nig) / gsz; return true;
;     DEV void operator()(const f32x4 (&acc)[2][2][4][2], const Unit& u, int wr, int wc, int fr, int fq) const {
;     ...
;                     const size_t p = (size_t)(row0 + ai * 128 + m * 16) * D + col0 + bj * 128;
;                     const f32x4 r0 = *(const f32x4*)(res + p), r1 = *(const f32x4*)(res + p + NS);
.LBB0_1977:
	s_lshl_b32 s100, s67, 8
	s_add_u32 s100, s100, s48
	v_lshrrev_b32_e32 v252, 1, v156
	v_lshlrev_b32_e32 v252, 4, v252
	v_add_u32_e32 v252, v252, v147
	v_add_u32_e32 v252, s100, v252
	s_lshl_b32 s101, s68, 8
	s_or_b32 s101, s101, s49
	s_lshl_b32 s101, s101, 2
	v_and_b32_e32 v253, 1, v156
	v_lshlrev_b32_e32 v253, 9, v253
	v_add_u32_e32 v253, s101, v253
	v_lshl_add_u32 v252, v252, 12, v253
	global_load_dword v255, v252, s[86:87]
	s_add_u32 s98, s86, 0x20000
	s_addc_u32 s99, s87, 0
	global_load_dword v255, v252, s[98:99]
	s_add_u32 s98, s86, 0x80000
	s_addc_u32 s99, s87, 0
	global_load_dword v255, v252, s[98:99]
	s_add_u32 s98, s86, 0xa0000
	s_addc_u32 s99, s87, 0
	global_load_dword v255, v252, s[98:99]
	s_add_i32 s46, s46, 1
	s_mul_i32 s4, s46, s54
	s_mul_hi_u32 s5, s46, s50
	s_add_i32 s5, s5, s4
	s_mul_i32 s4, s46, s50
	s_add_u32 s4, s4, s2
	s_addc_u32 s5, s5, s3
	v_cmp_gt_i64_e32 vcc, s[4:5], v[140:141]
	v_cmp_lt_i64_e64 s[6:7], s[4:5], v[138:139]
	s_cbranch_vccnz .LBB0_1983
	s_ashr_i32 s5, s4, 31
	s_lshr_b32 s5, s5, 29
	s_add_i32 s30, s4, s5
	s_and_b32 s5, s30, -8
	s_sub_i32 s31, s4, s5
	s_cmp_gt_i32 s31, -1
	s_mov_b64 s[4:5], -1
	s_cbranch_scc0 .LBB0_1980
	s_lshl_b32 s38, s31, 7
	s_mov_b64 s[4:5], 0
